# fold scalar loads merged; attention QK block: 8 K-fragment ds_reads issued up front into dead K-raw regs with counted lgkmcnt
# speedup vs baseline: 1.0139x; 1.0013x over previous
; __device__ __forceinline__ float bf_lo(unsigned u) { return __uint_as_float(u << 16); }
; __device__ __forceinline__ float bf_hi(unsigned u) { return __uint_as_float(u & 0xffff0000u); }
; __device__ __forceinline__ void phase_fold(const bf16_t* __restrict__ zt, bf16_t* __restrict__ zf, float* __restrict__ ph, const int nseq, const int S) {
;     ...
;       if (j <= Q4) {
;         const uint4 w1 = *(const uint4*)(a + j), w2 = *(const uint4*)(a + S - j - 8), w3 = *(const uint4*)(a + H - j - 8), w4 = *(const uint4*)(a + H + j);
;         const float s2 = (j > 0) ? __uint_as_float(((unsigned)a[S - j]) << 16) : 0.f;
;         const float s3 = __uint_as_float(((unsigned)a[H - j]) << 16);
;         const float v1[8] = {bf_lo(w1.x), bf_hi(w1.x), bf_lo(w1.y), bf_hi(w1.y), bf_lo(w1.z), bf_hi(w1.z), bf_lo(w1.w), bf_hi(w1.w)};
;         const float v2[8] = {s2, bf_hi(w2.w), bf_lo(w2.w), bf_hi(w2.z), bf_lo(w2.z), bf_hi(w2.y), bf_lo(w2.y), bf_hi(w2.x)};
;         const float v3[8] = {s3, bf_hi(w3.w), bf_lo(w3.w), bf_hi(w3.z), bf_lo(w3.z), bf_hi(w3.y), bf_lo(w3.y), bf_hi(w3.x)};
;         const float v4[8] = {bf_lo(w4.x), bf_hi(w4.x), bf_lo(w4.y), bf_hi(w4.y), bf_lo(w4.z), bf_hi(w4.z), bf_lo(w4.w), bf_hi(w4.w)};
.LBB0_326:
	v_mov_b32_e32 v2, v81
	v_cmp_ge_u32_e32 vcc, s13, v31
	v_mov_b32_e32 v3, v2
	v_mov_b64_e32 v[0:1], v[2:3]
	v_mov_b64_e32 v[6:7], v[2:3]
	v_mov_b64_e32 v[4:5], v[2:3]
	s_and_saveexec_b64 s[8:9], vcc
	s_xor_b64 s[96:97], exec, s[8:9]
	s_cbranch_execz .LBB0_325
	v_lshl_add_u64 v[0:1], v[38:39], 0, v[32:33]
	v_add_co_u32_e32 v0, vcc, 0x18180000, v0
	v_lshl_add_u64 v[4:5], v[44:45], 0, v[32:33]
	s_nop 0
	v_addc_co_u32_e32 v1, vcc, 0, v1, vcc
	v_add_co_u32_e32 v4, vcc, 0x1817f000, v4
	v_lshl_add_u64 v[8:9], v[42:43], 0, v[32:33]
	s_nop 0
	v_addc_co_u32_e32 v5, vcc, 0, v5, vcc
	v_add_co_u32_e32 v8, vcc, 0x1817f000, v8
	v_lshl_add_u64 v[12:13], v[40:41], 0, v[32:33]
	s_nop 0
	v_addc_co_u32_e32 v9, vcc, 0, v9, vcc
	v_add_co_u32_e32 v12, vcc, 0x18180000, v12
	global_load_dwordx4 v[0:3], v[0:1], off
	s_nop 0
	v_addc_co_u32_e32 v13, vcc, 0, v13, vcc
	global_load_dwordx4 v[4:7], v[4:5], off offset:4080
	v_cmp_eq_u32_e32 vcc, 0, v31
	global_load_dwordx4 v[8:11], v[8:9], off offset:4080
	v_cmp_ne_u32_e64 s[8:9], 0, v31
	global_load_dwordx4 v[12:15], v[12:13], off
	v_add_u32_e32 v80, s40, v46
	v_lshl_add_u64 v[102:103], v[80:81], 1, v[34:35]
	global_load_ushort v100, v[102:103], off
	v_mov_b32_e32 v52, 0
	s_and_saveexec_b64 s[18:19], s[8:9]
	s_cbranch_execz .LBB0_329
	v_add_u32_e32 v80, s17, v46
	v_lshl_add_u64 v[48:49], v[80:81], 1, v[34:35]
	global_load_ushort v48, v[48:49], off
	s_waitcnt vmcnt(0) lgkmcnt(0)
	v_lshlrev_b32_e32 v52, 16, v48
.LBB0_329:
	s_or_b64 exec, exec, s[18:19]
	s_waitcnt vmcnt(0) lgkmcnt(0)
	v_lshlrev_b32_e32 v54, 16, v0
	v_lshlrev_b32_e32 v53, 16, v12
	v_lshlrev_b32_e32 v55, 16, v100
	s_and_saveexec_b64 s[8:9], s[6:7]
	s_xor_b64 s[8:9], exec, s[8:9]
	s_cbranch_execz .LBB0_333
	v_pk_add_f32 v[48:49], v[54:55], v[52:53] neg_lo:[0,1] neg_hi:[0,1]
	s_and_saveexec_b64 s[18:19], vcc
	v_mov_b32_e32 v49, 0
	v_mov_b32_e32 v48, v49
	s_or_b64 exec, exec, s[18:19]

; #define LAS __attribute__((address_space(3)))
; __device__ __forceinline__ void phase_attention(bf16_t* __restrict__ qh, const bf16_t* __restrict__ kh, const bf16_t* __restrict__ vb, float* __restrict__ lse, LAS unsigned char* obuf, const int nseq, const int S) {
;     ...
; #pragma unroll
;       for (int i = 0; i < 8; ++i) *(LAS u32x4*)(tb + kw + i * (4 * 272)) = kraw[i];
;       bf16x8 kf[8];
; #pragma unroll
;       for (int kk = 0; kk < 8; ++kk) kf[kk] = *(const LAS bf16x8*)(tb + kr + 32 * kk);
;       f32x16 s;
; #pragma unroll
;       for (int e = 0; e < 16; ++e) s[e] = 0.f;
; #pragma unroll
;       for (int kk = 0; kk < 8; ++kk) s = __builtin_amdgcn_mfma_f32_32x32x16_bf16(kf[kk], qf[kk], s, 0, 0, 0);
;       if (j < jmax) { const bf16_t* kp = kt0 + (ptrdiff_t)(kb + 32) * 128;
; #pragma unroll
;         for (int i = 0; i < 8; ++i) kraw[i] = *(const u32x4*)(kp + i * 512); }
.LBB0_717:
	v_add_u32_e32 v183, v199, v193
	v_subrev_u32_e32 v68, 64, v183
	v_ashrrev_i32_e32 v68, 5, v68
	v_ashrrev_i32_e32 v69, 31, v68
	v_add_u32_e32 v64, v238, v241
	v_lshlrev_b64 v[68:69], 13, v[68:69]
	s_waitcnt vmcnt(0) lgkmcnt(0)
	ds_write_b128 v64, v[114:117]
	ds_write_b128 v64, v[118:121] offset:1088
	ds_write_b128 v64, v[122:125] offset:2176
	ds_write_b128 v64, v[126:129] offset:3264
	ds_write_b128 v64, v[130:133] offset:4352
	ds_write_b128 v64, v[134:137] offset:5440
	ds_write_b128 v64, v[138:141] offset:6528
	ds_write_b128 v64, v[142:145] offset:7616
	v_lshl_add_u64 v[68:69], v[218:219], 0, v[68:69]
	ds_read_b128 v[114:117], v247
	ds_read_b128 v[118:121], v247 offset:32
	ds_read_b128 v[122:125], v247 offset:64
	ds_read_b128 v[126:129], v247 offset:96
	ds_read_b128 v[130:133], v247 offset:128
	ds_read_b128 v[134:137], v247 offset:160
	ds_read_b128 v[138:141], v247 offset:192
	ds_read_b128 v[142:145], v247 offset:224
	global_load_dwordx4 v[146:149], v[68:69], off
	global_load_dwordx4 v[150:153], v[68:69], off offset:1024
	global_load_dwordx4 v[154:157], v[68:69], off offset:2048
	global_load_dwordx4 v[158:161], v[68:69], off offset:3072
	v_add_co_u32_e32 v68, vcc, s77, v68
	v_cmp_gt_i32_e64 s[4:5], v195, v197
	s_nop 0
	v_addc_co_u32_e32 v69, vcc, 0, v69, vcc
	global_load_dwordx4 v[162:165], v[68:69], off
	global_load_dwordx4 v[166:169], v[68:69], off offset:1024
	global_load_dwordx4 v[170:173], v[68:69], off offset:2048
	global_load_dwordx4 v[174:177], v[68:69], off offset:3072
	s_waitcnt lgkmcnt(7)
	v_mfma_f32_32x32x16_bf16 v[64:79], v[114:117], v[82:85], 0
	v_cmp_le_i32_e32 vcc, v195, v197
	s_waitcnt lgkmcnt(6)
	v_mfma_f32_32x32x16_bf16 v[64:79], v[118:121], v[86:89], v[64:79]
	s_waitcnt lgkmcnt(5)
	v_mfma_f32_32x32x16_bf16 v[64:79], v[122:125], v[90:93], v[64:79]
	s_waitcnt lgkmcnt(4)
	v_mfma_f32_32x32x16_bf16 v[64:79], v[126:129], v[94:97], v[64:79]
	s_waitcnt lgkmcnt(3)
	v_mfma_f32_32x32x16_bf16 v[64:79], v[130:133], v[98:101], v[64:79]
	s_waitcnt lgkmcnt(2)
	v_mfma_f32_32x32x16_bf16 v[64:79], v[134:137], v[102:105], v[64:79]
	s_waitcnt lgkmcnt(1)
	v_mfma_f32_32x32x16_bf16 v[64:79], v[138:141], v[106:109], v[64:79]
	s_waitcnt lgkmcnt(0)
	v_mfma_f32_32x32x16_bf16 v[64:79], v[142:145], v[110:113], v[64:79]
	s_and_saveexec_b64 s[44:45], vcc
	s_cbranch_execz .LBB0_716
	v_subrev_u32_e32 v114, 32, v183
	v_ashrrev_i32_e32 v115, 31, v114
	v_lshlrev_b64 v[114:115], 8, v[114:115]
	v_lshl_add_u64 v[130:131], v[214:215], 0, v[114:115]
	v_add_co_u32_e32 v142, vcc, 0x1000, v130
	global_load_dwordx4 v[114:117], v[130:131], off
	global_load_dwordx4 v[118:121], v[130:131], off offset:1024
	global_load_dwordx4 v[122:125], v[130:131], off offset:2048
	global_load_dwordx4 v[126:129], v[130:131], off offset:3072
	v_addc_co_u32_e32 v143, vcc, 0, v131, vcc
	global_load_dwordx4 v[130:133], v[142:143], off
	global_load_dwordx4 v[134:137], v[142:143], off offset:1024
	global_load_dwordx4 v[138:141], v[142:143], off offset:2048
	s_nop 0
	global_load_dwordx4 v[142:145], v[142:143], off offset:3072
	s_or_b64 exec, exec, s[44:45]
	s_waitcnt vmcnt(8)
	s_branch .Lattn_vready
